# prologue silu(c) LDS fill: 16 loads per thread issued together instead of one exposed round trip each
# speedup vs baseline: 1.0046x; 1.0046x over previous
.LBB0_16:
	global_load_dword v64, v[2:3], off
	v_lshl_add_u64 v[2:3], v[2:3], 0, s[6:7]
	global_load_dword v65, v[2:3], off
	v_lshl_add_u64 v[2:3], v[2:3], 0, s[6:7]
	global_load_dword v66, v[2:3], off
	v_lshl_add_u64 v[2:3], v[2:3], 0, s[6:7]
	global_load_dword v67, v[2:3], off
	v_lshl_add_u64 v[2:3], v[2:3], 0, s[6:7]
	global_load_dword v68, v[2:3], off
	v_lshl_add_u64 v[2:3], v[2:3], 0, s[6:7]
	global_load_dword v69, v[2:3], off
	v_lshl_add_u64 v[2:3], v[2:3], 0, s[6:7]
	global_load_dword v70, v[2:3], off
	v_lshl_add_u64 v[2:3], v[2:3], 0, s[6:7]
	global_load_dword v71, v[2:3], off
	v_lshl_add_u64 v[2:3], v[2:3], 0, s[6:7]
	global_load_dword v72, v[2:3], off
	v_lshl_add_u64 v[2:3], v[2:3], 0, s[6:7]
	global_load_dword v73, v[2:3], off
	v_lshl_add_u64 v[2:3], v[2:3], 0, s[6:7]
	global_load_dword v74, v[2:3], off
	v_lshl_add_u64 v[2:3], v[2:3], 0, s[6:7]
	global_load_dword v75, v[2:3], off
	v_lshl_add_u64 v[2:3], v[2:3], 0, s[6:7]
	global_load_dword v76, v[2:3], off
	v_lshl_add_u64 v[2:3], v[2:3], 0, s[6:7]
	global_load_dword v77, v[2:3], off
	v_lshl_add_u64 v[2:3], v[2:3], 0, s[6:7]
	global_load_dword v78, v[2:3], off
	v_lshl_add_u64 v[2:3], v[2:3], 0, s[6:7]
	global_load_dword v79, v[2:3], off
	s_waitcnt vmcnt(15)
	v_mov_b32_e32 v6, v64
	v_mul_f32_e32 v7, 0xbfb8aa3b, v6
	v_rndne_f32_e32 v8, v7
	v_fma_f32 v9, v6, s8, -v7
	v_sub_f32_e32 v7, v7, v8
	v_fmac_f32_e32 v9, 0xb2a5705f, v6
	v_add_f32_e32 v7, v7, v9
	v_cvt_i32_f32_e32 v8, v8
	v_exp_f32_e32 v7, v7
	v_cmp_nlt_f32_e32 vcc, s9, v6
	v_ldexp_f32 v7, v7, v8
	s_nop 0
	v_cndmask_b32_e32 v7, 0, v7, vcc
	v_cmp_ngt_f32_e32 vcc, s16, v6
	s_nop 1
	v_cndmask_b32_e32 v7, v5, v7, vcc
	v_add_f32_e32 v7, 1.0, v7
	v_div_scale_f32 v8, s[18:19], v7, v7, v6
	v_rcp_f32_e32 v9, v8
	v_div_scale_f32 v10, vcc, v6, v7, v6
	v_fma_f32 v11, -v8, v9, 1.0
	v_fmac_f32_e32 v9, v11, v9
	v_mul_f32_e32 v11, v10, v9
	v_fma_f32 v12, -v8, v11, v10
	v_fmac_f32_e32 v11, v12, v9
	v_fma_f32 v8, -v8, v11, v10
	v_div_fmas_f32 v8, v8, v9, v11
	v_div_fixup_f32 v6, v8, v7, v6
	ds_write_b32 v4, v6
	s_waitcnt vmcnt(14)
	v_mov_b32_e32 v6, v65
	v_mul_f32_e32 v7, 0xbfb8aa3b, v6
	v_rndne_f32_e32 v8, v7
	v_fma_f32 v9, v6, s8, -v7
	v_sub_f32_e32 v7, v7, v8
	v_fmac_f32_e32 v9, 0xb2a5705f, v6
	v_add_f32_e32 v7, v7, v9
	v_cvt_i32_f32_e32 v8, v8
	v_exp_f32_e32 v7, v7
	v_cmp_nlt_f32_e32 vcc, s9, v6
	v_ldexp_f32 v7, v7, v8
	s_nop 0
	v_cndmask_b32_e32 v7, 0, v7, vcc
	v_cmp_ngt_f32_e32 vcc, s16, v6
	s_nop 1
	v_cndmask_b32_e32 v7, v5, v7, vcc
	v_add_f32_e32 v7, 1.0, v7
	v_div_scale_f32 v8, s[18:19], v7, v7, v6
	v_rcp_f32_e32 v9, v8
	v_div_scale_f32 v10, vcc, v6, v7, v6
	v_fma_f32 v11, -v8, v9, 1.0
	v_fmac_f32_e32 v9, v11, v9
	v_mul_f32_e32 v11, v10, v9
	v_fma_f32 v12, -v8, v11, v10
	v_fmac_f32_e32 v11, v12, v9
	v_fma_f32 v8, -v8, v11, v10
	v_div_fmas_f32 v8, v8, v9, v11
	v_div_fixup_f32 v6, v8, v7, v6
	ds_write_b32 v4, v6 offset:2048
	s_waitcnt vmcnt(13)
	v_mov_b32_e32 v6, v66
	v_mul_f32_e32 v7, 0xbfb8aa3b, v6
	v_rndne_f32_e32 v8, v7
	v_fma_f32 v9, v6, s8, -v7
	v_sub_f32_e32 v7, v7, v8
	v_fmac_f32_e32 v9, 0xb2a5705f, v6
	v_add_f32_e32 v7, v7, v9
	v_cvt_i32_f32_e32 v8, v8
	v_exp_f32_e32 v7, v7
	v_cmp_nlt_f32_e32 vcc, s9, v6
	v_ldexp_f32 v7, v7, v8
	s_nop 0
	v_cndmask_b32_e32 v7, 0, v7, vcc
	v_cmp_ngt_f32_e32 vcc, s16, v6
	s_nop 1
	v_cndmask_b32_e32 v7, v5, v7, vcc
	v_add_f32_e32 v7, 1.0, v7
	v_div_scale_f32 v8, s[18:19], v7, v7, v6
	v_rcp_f32_e32 v9, v8
	v_div_scale_f32 v10, vcc, v6, v7, v6
	v_fma_f32 v11, -v8, v9, 1.0
	v_fmac_f32_e32 v9, v11, v9
	v_mul_f32_e32 v11, v10, v9
	v_fma_f32 v12, -v8, v11, v10
	v_fmac_f32_e32 v11, v12, v9
	v_fma_f32 v8, -v8, v11, v10
	v_div_fmas_f32 v8, v8, v9, v11
	v_div_fixup_f32 v6, v8, v7, v6
	ds_write_b32 v4, v6 offset:4096
	s_waitcnt vmcnt(12)
	v_mov_b32_e32 v6, v67
	v_mul_f32_e32 v7, 0xbfb8aa3b, v6
	v_rndne_f32_e32 v8, v7
	v_fma_f32 v9, v6, s8, -v7
	v_sub_f32_e32 v7, v7, v8
	v_fmac_f32_e32 v9, 0xb2a5705f, v6
	v_add_f32_e32 v7, v7, v9
	v_cvt_i32_f32_e32 v8, v8
	v_exp_f32_e32 v7, v7
	v_cmp_nlt_f32_e32 vcc, s9, v6
	v_ldexp_f32 v7, v7, v8
	s_nop 0
	v_cndmask_b32_e32 v7, 0, v7, vcc
	v_cmp_ngt_f32_e32 vcc, s16, v6
	s_nop 1
	v_cndmask_b32_e32 v7, v5, v7, vcc
	v_add_f32_e32 v7, 1.0, v7
	v_div_scale_f32 v8, s[18:19], v7, v7, v6
	v_rcp_f32_e32 v9, v8
	v_div_scale_f32 v10, vcc, v6, v7, v6
	v_fma_f32 v11, -v8, v9, 1.0
	v_fmac_f32_e32 v9, v11, v9
	v_mul_f32_e32 v11, v10, v9
	v_fma_f32 v12, -v8, v11, v10
	v_fmac_f32_e32 v11, v12, v9
	v_fma_f32 v8, -v8, v11, v10
	v_div_fmas_f32 v8, v8, v9, v11
	v_div_fixup_f32 v6, v8, v7, v6
	ds_write_b32 v4, v6 offset:6144
	s_waitcnt vmcnt(11)
	v_mov_b32_e32 v6, v68
	v_mul_f32_e32 v7, 0xbfb8aa3b, v6
	v_rndne_f32_e32 v8, v7
	v_fma_f32 v9, v6, s8, -v7
	v_sub_f32_e32 v7, v7, v8
	v_fmac_f32_e32 v9, 0xb2a5705f, v6
	v_add_f32_e32 v7, v7, v9
	v_cvt_i32_f32_e32 v8, v8
	v_exp_f32_e32 v7, v7
	v_cmp_nlt_f32_e32 vcc, s9, v6
	v_ldexp_f32 v7, v7, v8
	s_nop 0
	v_cndmask_b32_e32 v7, 0, v7, vcc
	v_cmp_ngt_f32_e32 vcc, s16, v6
	s_nop 1
	v_cndmask_b32_e32 v7, v5, v7, vcc
	v_add_f32_e32 v7, 1.0, v7
	v_div_scale_f32 v8, s[18:19], v7, v7, v6
	v_rcp_f32_e32 v9, v8
	v_div_scale_f32 v10, vcc, v6, v7, v6
	v_fma_f32 v11, -v8, v9, 1.0
	v_fmac_f32_e32 v9, v11, v9
	v_mul_f32_e32 v11, v10, v9
	v_fma_f32 v12, -v8, v11, v10
	v_fmac_f32_e32 v11, v12, v9
	v_fma_f32 v8, -v8, v11, v10
	v_div_fmas_f32 v8, v8, v9, v11
	v_div_fixup_f32 v6, v8, v7, v6
	ds_write_b32 v4, v6 offset:8192
	s_waitcnt vmcnt(10)
	v_mov_b32_e32 v6, v69
	v_mul_f32_e32 v7, 0xbfb8aa3b, v6
	v_rndne_f32_e32 v8, v7
	v_fma_f32 v9, v6, s8, -v7
	v_sub_f32_e32 v7, v7, v8
	v_fmac_f32_e32 v9, 0xb2a5705f, v6
	v_add_f32_e32 v7, v7, v9
	v_cvt_i32_f32_e32 v8, v8
	v_exp_f32_e32 v7, v7
	v_cmp_nlt_f32_e32 vcc, s9, v6
	v_ldexp_f32 v7, v7, v8
	s_nop 0
	v_cndmask_b32_e32 v7, 0, v7, vcc
	v_cmp_ngt_f32_e32 vcc, s16, v6
	s_nop 1
	v_cndmask_b32_e32 v7, v5, v7, vcc
	v_add_f32_e32 v7, 1.0, v7
	v_div_scale_f32 v8, s[18:19], v7, v7, v6
	v_rcp_f32_e32 v9, v8
	v_div_scale_f32 v10, vcc, v6, v7, v6
	v_fma_f32 v11, -v8, v9, 1.0
	v_fmac_f32_e32 v9, v11, v9
	v_mul_f32_e32 v11, v10, v9
	v_fma_f32 v12, -v8, v11, v10
	v_fmac_f32_e32 v11, v12, v9
	v_fma_f32 v8, -v8, v11, v10
	v_div_fmas_f32 v8, v8, v9, v11
	v_div_fixup_f32 v6, v8, v7, v6
	ds_write_b32 v4, v6 offset:10240
	s_waitcnt vmcnt(9)
	v_mov_b32_e32 v6, v70
	v_mul_f32_e32 v7, 0xbfb8aa3b, v6
	v_rndne_f32_e32 v8, v7
	v_fma_f32 v9, v6, s8, -v7
	v_sub_f32_e32 v7, v7, v8
	v_fmac_f32_e32 v9, 0xb2a5705f, v6
	v_add_f32_e32 v7, v7, v9
	v_cvt_i32_f32_e32 v8, v8
	v_exp_f32_e32 v7, v7
	v_cmp_nlt_f32_e32 vcc, s9, v6
	v_ldexp_f32 v7, v7, v8
	s_nop 0
	v_cndmask_b32_e32 v7, 0, v7, vcc
	v_cmp_ngt_f32_e32 vcc, s16, v6
	s_nop 1
	v_cndmask_b32_e32 v7, v5, v7, vcc
	v_add_f32_e32 v7, 1.0, v7
	v_div_scale_f32 v8, s[18:19], v7, v7, v6
	v_rcp_f32_e32 v9, v8
	v_div_scale_f32 v10, vcc, v6, v7, v6
	v_fma_f32 v11, -v8, v9, 1.0
	v_fmac_f32_e32 v9, v11, v9
	v_mul_f32_e32 v11, v10, v9
	v_fma_f32 v12, -v8, v11, v10
	v_fmac_f32_e32 v11, v12, v9
	v_fma_f32 v8, -v8, v11, v10
	v_div_fmas_f32 v8, v8, v9, v11
	v_div_fixup_f32 v6, v8, v7, v6
	ds_write_b32 v4, v6 offset:12288
	s_waitcnt vmcnt(8)
	v_mov_b32_e32 v6, v71
	v_mul_f32_e32 v7, 0xbfb8aa3b, v6
	v_rndne_f32_e32 v8, v7
	v_fma_f32 v9, v6, s8, -v7
	v_sub_f32_e32 v7, v7, v8
	v_fmac_f32_e32 v9, 0xb2a5705f, v6
	v_add_f32_e32 v7, v7, v9
	v_cvt_i32_f32_e32 v8, v8
	v_exp_f32_e32 v7, v7
	v_cmp_nlt_f32_e32 vcc, s9, v6
	v_ldexp_f32 v7, v7, v8
	s_nop 0
	v_cndmask_b32_e32 v7, 0, v7, vcc
	v_cmp_ngt_f32_e32 vcc, s16, v6
	s_nop 1
	v_cndmask_b32_e32 v7, v5, v7, vcc
	v_add_f32_e32 v7, 1.0, v7
	v_div_scale_f32 v8, s[18:19], v7, v7, v6
	v_rcp_f32_e32 v9, v8
	v_div_scale_f32 v10, vcc, v6, v7, v6
	v_fma_f32 v11, -v8, v9, 1.0
	v_fmac_f32_e32 v9, v11, v9
	v_mul_f32_e32 v11, v10, v9
	v_fma_f32 v12, -v8, v11, v10
	v_fmac_f32_e32 v11, v12, v9
	v_fma_f32 v8, -v8, v11, v10
	v_div_fmas_f32 v8, v8, v9, v11
	v_div_fixup_f32 v6, v8, v7, v6
	ds_write_b32 v4, v6 offset:14336
	s_waitcnt vmcnt(7)
	v_mov_b32_e32 v6, v72
	v_mul_f32_e32 v7, 0xbfb8aa3b, v6
	v_rndne_f32_e32 v8, v7
	v_fma_f32 v9, v6, s8, -v7
	v_sub_f32_e32 v7, v7, v8
	v_fmac_f32_e32 v9, 0xb2a5705f, v6
	v_add_f32_e32 v7, v7, v9
	v_cvt_i32_f32_e32 v8, v8
	v_exp_f32_e32 v7, v7
	v_cmp_nlt_f32_e32 vcc, s9, v6
	v_ldexp_f32 v7, v7, v8
	s_nop 0
	v_cndmask_b32_e32 v7, 0, v7, vcc
	v_cmp_ngt_f32_e32 vcc, s16, v6
	s_nop 1
	v_cndmask_b32_e32 v7, v5, v7, vcc
	v_add_f32_e32 v7, 1.0, v7
	v_div_scale_f32 v8, s[18:19], v7, v7, v6
	v_rcp_f32_e32 v9, v8
	v_div_scale_f32 v10, vcc, v6, v7, v6
	v_fma_f32 v11, -v8, v9, 1.0
	v_fmac_f32_e32 v9, v11, v9
	v_mul_f32_e32 v11, v10, v9
	v_fma_f32 v12, -v8, v11, v10
	v_fmac_f32_e32 v11, v12, v9
	v_fma_f32 v8, -v8, v11, v10
	v_div_fmas_f32 v8, v8, v9, v11
	v_div_fixup_f32 v6, v8, v7, v6
	ds_write_b32 v4, v6 offset:16384
	s_waitcnt vmcnt(6)
	v_mov_b32_e32 v6, v73
	v_mul_f32_e32 v7, 0xbfb8aa3b, v6
	v_rndne_f32_e32 v8, v7
	v_fma_f32 v9, v6, s8, -v7
	v_sub_f32_e32 v7, v7, v8
	v_fmac_f32_e32 v9, 0xb2a5705f, v6
	v_add_f32_e32 v7, v7, v9
	v_cvt_i32_f32_e32 v8, v8
	v_exp_f32_e32 v7, v7
	v_cmp_nlt_f32_e32 vcc, s9, v6
	v_ldexp_f32 v7, v7, v8
	s_nop 0
	v_cndmask_b32_e32 v7, 0, v7, vcc
	v_cmp_ngt_f32_e32 vcc, s16, v6
	s_nop 1
	v_cndmask_b32_e32 v7, v5, v7, vcc
	v_add_f32_e32 v7, 1.0, v7
	v_div_scale_f32 v8, s[18:19], v7, v7, v6
	v_rcp_f32_e32 v9, v8
	v_div_scale_f32 v10, vcc, v6, v7, v6
	v_fma_f32 v11, -v8, v9, 1.0
	v_fmac_f32_e32 v9, v11, v9
	v_mul_f32_e32 v11, v10, v9
	v_fma_f32 v12, -v8, v11, v10
	v_fmac_f32_e32 v11, v12, v9
	v_fma_f32 v8, -v8, v11, v10
	v_div_fmas_f32 v8, v8, v9, v11
	v_div_fixup_f32 v6, v8, v7, v6
	ds_write_b32 v4, v6 offset:18432
	s_waitcnt vmcnt(5)
	v_mov_b32_e32 v6, v74
	v_mul_f32_e32 v7, 0xbfb8aa3b, v6
	v_rndne_f32_e32 v8, v7
	v_fma_f32 v9, v6, s8, -v7
	v_sub_f32_e32 v7, v7, v8
	v_fmac_f32_e32 v9, 0xb2a5705f, v6
	v_add_f32_e32 v7, v7, v9
	v_cvt_i32_f32_e32 v8, v8
	v_exp_f32_e32 v7, v7
	v_cmp_nlt_f32_e32 vcc, s9, v6
	v_ldexp_f32 v7, v7, v8
	s_nop 0
	v_cndmask_b32_e32 v7, 0, v7, vcc
	v_cmp_ngt_f32_e32 vcc, s16, v6
	s_nop 1
	v_cndmask_b32_e32 v7, v5, v7, vcc
	v_add_f32_e32 v7, 1.0, v7
	v_div_scale_f32 v8, s[18:19], v7, v7, v6
	v_rcp_f32_e32 v9, v8
	v_div_scale_f32 v10, vcc, v6, v7, v6
	v_fma_f32 v11, -v8, v9, 1.0
	v_fmac_f32_e32 v9, v11, v9
	v_mul_f32_e32 v11, v10, v9
	v_fma_f32 v12, -v8, v11, v10
	v_fmac_f32_e32 v11, v12, v9
	v_fma_f32 v8, -v8, v11, v10
	v_div_fmas_f32 v8, v8, v9, v11
	v_div_fixup_f32 v6, v8, v7, v6
	ds_write_b32 v4, v6 offset:20480
	s_waitcnt vmcnt(4)
	v_mov_b32_e32 v6, v75
	v_mul_f32_e32 v7, 0xbfb8aa3b, v6
	v_rndne_f32_e32 v8, v7
	v_fma_f32 v9, v6, s8, -v7
	v_sub_f32_e32 v7, v7, v8
	v_fmac_f32_e32 v9, 0xb2a5705f, v6
	v_add_f32_e32 v7, v7, v9
	v_cvt_i32_f32_e32 v8, v8
	v_exp_f32_e32 v7, v7
	v_cmp_nlt_f32_e32 vcc, s9, v6
	v_ldexp_f32 v7, v7, v8
	s_nop 0
	v_cndmask_b32_e32 v7, 0, v7, vcc
	v_cmp_ngt_f32_e32 vcc, s16, v6
	s_nop 1
	v_cndmask_b32_e32 v7, v5, v7, vcc
	v_add_f32_e32 v7, 1.0, v7
	v_div_scale_f32 v8, s[18:19], v7, v7, v6
	v_rcp_f32_e32 v9, v8
	v_div_scale_f32 v10, vcc, v6, v7, v6
	v_fma_f32 v11, -v8, v9, 1.0
	v_fmac_f32_e32 v9, v11, v9
	v_mul_f32_e32 v11, v10, v9
	v_fma_f32 v12, -v8, v11, v10
	v_fmac_f32_e32 v11, v12, v9
	v_fma_f32 v8, -v8, v11, v10
	v_div_fmas_f32 v8, v8, v9, v11
	v_div_fixup_f32 v6, v8, v7, v6
	ds_write_b32 v4, v6 offset:22528
	s_waitcnt vmcnt(3)
	v_mov_b32_e32 v6, v76
	v_mul_f32_e32 v7, 0xbfb8aa3b, v6
	v_rndne_f32_e32 v8, v7
	v_fma_f32 v9, v6, s8, -v7
	v_sub_f32_e32 v7, v7, v8
	v_fmac_f32_e32 v9, 0xb2a5705f, v6
	v_add_f32_e32 v7, v7, v9
	v_cvt_i32_f32_e32 v8, v8
	v_exp_f32_e32 v7, v7
	v_cmp_nlt_f32_e32 vcc, s9, v6
	v_ldexp_f32 v7, v7, v8
	s_nop 0
	v_cndmask_b32_e32 v7, 0, v7, vcc
	v_cmp_ngt_f32_e32 vcc, s16, v6
	s_nop 1
	v_cndmask_b32_e32 v7, v5, v7, vcc
	v_add_f32_e32 v7, 1.0, v7
	v_div_scale_f32 v8, s[18:19], v7, v7, v6
	v_rcp_f32_e32 v9, v8
	v_div_scale_f32 v10, vcc, v6, v7, v6
	v_fma_f32 v11, -v8, v9, 1.0
	v_fmac_f32_e32 v9, v11, v9
	v_mul_f32_e32 v11, v10, v9
	v_fma_f32 v12, -v8, v11, v10
	v_fmac_f32_e32 v11, v12, v9
	v_fma_f32 v8, -v8, v11, v10
	v_div_fmas_f32 v8, v8, v9, v11
	v_div_fixup_f32 v6, v8, v7, v6
	ds_write_b32 v4, v6 offset:24576
	s_waitcnt vmcnt(2)
	v_mov_b32_e32 v6, v77
	v_mul_f32_e32 v7, 0xbfb8aa3b, v6
	v_rndne_f32_e32 v8, v7
	v_fma_f32 v9, v6, s8, -v7
	v_sub_f32_e32 v7, v7, v8
	v_fmac_f32_e32 v9, 0xb2a5705f, v6
	v_add_f32_e32 v7, v7, v9
	v_cvt_i32_f32_e32 v8, v8
	v_exp_f32_e32 v7, v7
	v_cmp_nlt_f32_e32 vcc, s9, v6
	v_ldexp_f32 v7, v7, v8
	s_nop 0
	v_cndmask_b32_e32 v7, 0, v7, vcc
	v_cmp_ngt_f32_e32 vcc, s16, v6
	s_nop 1
	v_cndmask_b32_e32 v7, v5, v7, vcc
	v_add_f32_e32 v7, 1.0, v7
	v_div_scale_f32 v8, s[18:19], v7, v7, v6
	v_rcp_f32_e32 v9, v8
	v_div_scale_f32 v10, vcc, v6, v7, v6
	v_fma_f32 v11, -v8, v9, 1.0
	v_fmac_f32_e32 v9, v11, v9
	v_mul_f32_e32 v11, v10, v9
	v_fma_f32 v12, -v8, v11, v10
	v_fmac_f32_e32 v11, v12, v9
	v_fma_f32 v8, -v8, v11, v10
	v_div_fmas_f32 v8, v8, v9, v11
	v_div_fixup_f32 v6, v8, v7, v6
	ds_write_b32 v4, v6 offset:26624
	s_waitcnt vmcnt(1)
	v_mov_b32_e32 v6, v78
	v_mul_f32_e32 v7, 0xbfb8aa3b, v6
	v_rndne_f32_e32 v8, v7
	v_fma_f32 v9, v6, s8, -v7
	v_sub_f32_e32 v7, v7, v8
	v_fmac_f32_e32 v9, 0xb2a5705f, v6
	v_add_f32_e32 v7, v7, v9
	v_cvt_i32_f32_e32 v8, v8
	v_exp_f32_e32 v7, v7
	v_cmp_nlt_f32_e32 vcc, s9, v6
	v_ldexp_f32 v7, v7, v8
	s_nop 0
	v_cndmask_b32_e32 v7, 0, v7, vcc
	v_cmp_ngt_f32_e32 vcc, s16, v6
	s_nop 1
	v_cndmask_b32_e32 v7, v5, v7, vcc
	v_add_f32_e32 v7, 1.0, v7
	v_div_scale_f32 v8, s[18:19], v7, v7, v6
	v_rcp_f32_e32 v9, v8
	v_div_scale_f32 v10, vcc, v6, v7, v6
	v_fma_f32 v11, -v8, v9, 1.0
	v_fmac_f32_e32 v9, v11, v9
	v_mul_f32_e32 v11, v10, v9
	v_fma_f32 v12, -v8, v11, v10
	v_fmac_f32_e32 v11, v12, v9
	v_fma_f32 v8, -v8, v11, v10
	v_div_fmas_f32 v8, v8, v9, v11
	v_div_fixup_f32 v6, v8, v7, v6
	ds_write_b32 v4, v6 offset:28672
	s_waitcnt vmcnt(0)
	v_mov_b32_e32 v6, v79
	v_mul_f32_e32 v7, 0xbfb8aa3b, v6
	v_rndne_f32_e32 v8, v7
	v_fma_f32 v9, v6, s8, -v7
	v_sub_f32_e32 v7, v7, v8
	v_fmac_f32_e32 v9, 0xb2a5705f, v6
	v_add_f32_e32 v7, v7, v9
	v_cvt_i32_f32_e32 v8, v8
	v_exp_f32_e32 v7, v7
	v_cmp_nlt_f32_e32 vcc, s9, v6
	v_ldexp_f32 v7, v7, v8
	s_nop 0
	v_cndmask_b32_e32 v7, 0, v7, vcc
	v_cmp_ngt_f32_e32 vcc, s16, v6
	s_nop 1
	v_cndmask_b32_e32 v7, v5, v7, vcc
	v_add_f32_e32 v7, 1.0, v7
	v_div_scale_f32 v8, s[18:19], v7, v7, v6
	v_rcp_f32_e32 v9, v8
	v_div_scale_f32 v10, vcc, v6, v7, v6
	v_fma_f32 v11, -v8, v9, 1.0
	v_fmac_f32_e32 v9, v11, v9
	v_mul_f32_e32 v11, v10, v9
	v_fma_f32 v12, -v8, v11, v10
	v_fmac_f32_e32 v11, v12, v9
	v_fma_f32 v8, -v8, v11, v10
	v_div_fmas_f32 v8, v8, v9, v11
	v_div_fixup_f32 v6, v8, v7, v6
	ds_write_b32 v4, v6 offset:30720
